# stack19: stack18 + phase-0 modulation unit: GEMV weight-row loads double-buffered a full iteration ahead, silu table loads issued together, table reused by a workgroup's second unit
# baseline (speedup 1.0000x reference)
; DI float fexp2(float x) { return __builtin_amdgcn_exp2f(x); }
; DI void mod_unit(const Params& p, int l, int cgi, ldsp_t smem) {
;     ...
;     for (int i = tid; i < 5 * 1024; i += 512) {
;         const int cnd = i >> 10, k = i & 1023;
;         const float v = cnd < 4 ? p.c[cnd * 1024 + k] : p.c_ctx[k];
;         s[i] = v / (1.f + fexp2(-LOG2E * v));
;     }
;     __syncthreads();
.LBB0_421:
	v_mov_b32_e32 v24, v252
	s_movk_i32 s4, 0x13ff
	s_nop 0
	v_cmp_lt_i32_e32 vcc, s4, v24
	v_lshlrev_b32_e32 v2, 2, v24
	s_and_saveexec_b64 s[4:5], vcc
	s_xor_b64 s[4:5], exec, s[4:5]
	v_lshlrev_b32_e32 v2, 2, v24
	s_andn2_saveexec_b64 s[4:5], s[4:5]
	s_cmpk_ge_i32 s10, 0x100
	s_cbranch_scc1 .LBB0_427
	s_cbranch_execz .LBB0_427
	v_ashrrev_i32_e32 v25, 31, v24
	v_lshl_add_u64 v[0:1], v[24:25], 2, s[14:15]
	s_mov_b64 s[6:7], 0
	v_mov_b32_e32 v3, v2
	s_waitcnt lgkmcnt(5)
	v_mov_b32_e32 v4, v24
	s_waitcnt lgkmcnt(0)
	v_add_u32_e32 v111, 0x1000, v2
	v_add_u32_e32 v112, 0x2000, v2
	v_add_u32_e32 v113, 0x3000, v2
	global_load_dword v100, v2, s[14:15]
	global_load_dword v101, v2, s[14:15] offset:2048
	global_load_dword v102, v111, s[14:15]
	global_load_dword v103, v111, s[14:15] offset:2048
	global_load_dword v104, v112, s[14:15]
	global_load_dword v105, v112, s[14:15] offset:2048
	global_load_dword v106, v113, s[14:15]
	global_load_dword v107, v113, s[14:15] offset:2048
	global_load_dword v108, v2, s[18:19]
	global_load_dword v109, v2, s[18:19] offset:2048
	s_waitcnt vmcnt(9)
	v_mov_b32_e32 v5, v100
	v_mul_f32_e32 v6, 0xbfb8aa3b, v5
	v_exp_f32_e32 v6, v6
	s_nop 0
	v_add_f32_e32 v6, 1.0, v6
	v_div_scale_f32 v7, s[8:9], v6, v6, v5
	v_rcp_f32_e32 v8, v7
	v_div_scale_f32 v9, vcc, v5, v6, v5
	v_fma_f32 v10, -v7, v8, 1.0
	v_fmac_f32_e32 v8, v10, v8
	v_mul_f32_e32 v10, v9, v8
	v_fma_f32 v11, -v7, v10, v9
	v_fmac_f32_e32 v10, v11, v8
	v_fma_f32 v7, -v7, v10, v9
	v_div_fmas_f32 v7, v7, v8, v10
	v_div_fixup_f32 v5, v7, v6, v5
	ds_write_b32 v2, v5
	s_waitcnt vmcnt(8)
	v_mov_b32_e32 v5, v101
	v_mul_f32_e32 v6, 0xbfb8aa3b, v5
	v_exp_f32_e32 v6, v6
	s_nop 0
	v_add_f32_e32 v6, 1.0, v6
	v_div_scale_f32 v7, s[8:9], v6, v6, v5
	v_rcp_f32_e32 v8, v7
	v_div_scale_f32 v9, vcc, v5, v6, v5
	v_fma_f32 v10, -v7, v8, 1.0
	v_fmac_f32_e32 v8, v10, v8
	v_mul_f32_e32 v10, v9, v8
	v_fma_f32 v11, -v7, v10, v9
	v_fmac_f32_e32 v10, v11, v8
	v_fma_f32 v7, -v7, v10, v9
	v_div_fmas_f32 v7, v7, v8, v10
	v_div_fixup_f32 v5, v7, v6, v5
	ds_write_b32 v2, v5 offset:2048
	s_waitcnt vmcnt(7)
	v_mov_b32_e32 v5, v102
	v_mul_f32_e32 v6, 0xbfb8aa3b, v5
	v_exp_f32_e32 v6, v6
	s_nop 0
	v_add_f32_e32 v6, 1.0, v6
	v_div_scale_f32 v7, s[8:9], v6, v6, v5
	v_rcp_f32_e32 v8, v7
	v_div_scale_f32 v9, vcc, v5, v6, v5
	v_fma_f32 v10, -v7, v8, 1.0
	v_fmac_f32_e32 v8, v10, v8
	v_mul_f32_e32 v10, v9, v8
	v_fma_f32 v11, -v7, v10, v9
	v_fmac_f32_e32 v10, v11, v8
	v_fma_f32 v7, -v7, v10, v9
	v_div_fmas_f32 v7, v7, v8, v10
	v_div_fixup_f32 v5, v7, v6, v5
	ds_write_b32 v2, v5 offset:4096
	s_waitcnt vmcnt(6)
	v_mov_b32_e32 v5, v103
	v_mul_f32_e32 v6, 0xbfb8aa3b, v5
	v_exp_f32_e32 v6, v6
	s_nop 0
	v_add_f32_e32 v6, 1.0, v6
	v_div_scale_f32 v7, s[8:9], v6, v6, v5
	v_rcp_f32_e32 v8, v7
	v_div_scale_f32 v9, vcc, v5, v6, v5
	v_fma_f32 v10, -v7, v8, 1.0
	v_fmac_f32_e32 v8, v10, v8
	v_mul_f32_e32 v10, v9, v8
	v_fma_f32 v11, -v7, v10, v9
	v_fmac_f32_e32 v10, v11, v8
	v_fma_f32 v7, -v7, v10, v9
	v_div_fmas_f32 v7, v7, v8, v10
	v_div_fixup_f32 v5, v7, v6, v5
	ds_write_b32 v2, v5 offset:6144
	s_waitcnt vmcnt(5)
	v_mov_b32_e32 v5, v104
	v_mul_f32_e32 v6, 0xbfb8aa3b, v5
	v_exp_f32_e32 v6, v6
	s_nop 0
	v_add_f32_e32 v6, 1.0, v6
	v_div_scale_f32 v7, s[8:9], v6, v6, v5
	v_rcp_f32_e32 v8, v7
	v_div_scale_f32 v9, vcc, v5, v6, v5
	v_fma_f32 v10, -v7, v8, 1.0
	v_fmac_f32_e32 v8, v10, v8
	v_mul_f32_e32 v10, v9, v8
	v_fma_f32 v11, -v7, v10, v9
	v_fmac_f32_e32 v10, v11, v8
	v_fma_f32 v7, -v7, v10, v9
	v_div_fmas_f32 v7, v7, v8, v10
	v_div_fixup_f32 v5, v7, v6, v5
	ds_write_b32 v2, v5 offset:8192
	s_waitcnt vmcnt(4)
	v_mov_b32_e32 v5, v105
	v_mul_f32_e32 v6, 0xbfb8aa3b, v5
	v_exp_f32_e32 v6, v6
	s_nop 0
	v_add_f32_e32 v6, 1.0, v6
	v_div_scale_f32 v7, s[8:9], v6, v6, v5
	v_rcp_f32_e32 v8, v7
	v_div_scale_f32 v9, vcc, v5, v6, v5
	v_fma_f32 v10, -v7, v8, 1.0
	v_fmac_f32_e32 v8, v10, v8
	v_mul_f32_e32 v10, v9, v8
	v_fma_f32 v11, -v7, v10, v9
	v_fmac_f32_e32 v10, v11, v8
	v_fma_f32 v7, -v7, v10, v9
	v_div_fmas_f32 v7, v7, v8, v10
	v_div_fixup_f32 v5, v7, v6, v5
	ds_write_b32 v2, v5 offset:10240
	s_waitcnt vmcnt(3)
	v_mov_b32_e32 v5, v106
	v_mul_f32_e32 v6, 0xbfb8aa3b, v5
	v_exp_f32_e32 v6, v6
	s_nop 0
	v_add_f32_e32 v6, 1.0, v6
	v_div_scale_f32 v7, s[8:9], v6, v6, v5
	v_rcp_f32_e32 v8, v7
	v_div_scale_f32 v9, vcc, v5, v6, v5
	v_fma_f32 v10, -v7, v8, 1.0
	v_fmac_f32_e32 v8, v10, v8
	v_mul_f32_e32 v10, v9, v8
	v_fma_f32 v11, -v7, v10, v9
	v_fmac_f32_e32 v10, v11, v8
	v_fma_f32 v7, -v7, v10, v9
	v_div_fmas_f32 v7, v7, v8, v10
	v_div_fixup_f32 v5, v7, v6, v5
	ds_write_b32 v2, v5 offset:12288
	s_waitcnt vmcnt(2)
	v_mov_b32_e32 v5, v107
	v_mul_f32_e32 v6, 0xbfb8aa3b, v5
	v_exp_f32_e32 v6, v6
	s_nop 0
	v_add_f32_e32 v6, 1.0, v6
	v_div_scale_f32 v7, s[8:9], v6, v6, v5
	v_rcp_f32_e32 v8, v7
	v_div_scale_f32 v9, vcc, v5, v6, v5
	v_fma_f32 v10, -v7, v8, 1.0
	v_fmac_f32_e32 v8, v10, v8
	v_mul_f32_e32 v10, v9, v8
	v_fma_f32 v11, -v7, v10, v9
	v_fmac_f32_e32 v10, v11, v8
	v_fma_f32 v7, -v7, v10, v9
	v_div_fmas_f32 v7, v7, v8, v10
	v_div_fixup_f32 v5, v7, v6, v5
	ds_write_b32 v2, v5 offset:14336
	s_waitcnt vmcnt(1)
	v_mov_b32_e32 v5, v108
	v_mul_f32_e32 v6, 0xbfb8aa3b, v5
	v_exp_f32_e32 v6, v6
	s_nop 0
	v_add_f32_e32 v6, 1.0, v6
	v_div_scale_f32 v7, s[8:9], v6, v6, v5
	v_rcp_f32_e32 v8, v7
	v_div_scale_f32 v9, vcc, v5, v6, v5
	v_fma_f32 v10, -v7, v8, 1.0
	v_fmac_f32_e32 v8, v10, v8
	v_mul_f32_e32 v10, v9, v8
	v_fma_f32 v11, -v7, v10, v9
	v_fmac_f32_e32 v10, v11, v8
	v_fma_f32 v7, -v7, v10, v9
	v_div_fmas_f32 v7, v7, v8, v10
	v_div_fixup_f32 v5, v7, v6, v5
	ds_write_b32 v2, v5 offset:16384
	s_waitcnt vmcnt(0)
	v_mov_b32_e32 v5, v109
	v_mul_f32_e32 v6, 0xbfb8aa3b, v5
	v_exp_f32_e32 v6, v6
	s_nop 0
	v_add_f32_e32 v6, 1.0, v6
	v_div_scale_f32 v7, s[8:9], v6, v6, v5
	v_rcp_f32_e32 v8, v7
	v_div_scale_f32 v9, vcc, v5, v6, v5
	v_fma_f32 v10, -v7, v8, 1.0
	v_fmac_f32_e32 v8, v10, v8
	v_mul_f32_e32 v10, v9, v8
	v_fma_f32 v11, -v7, v10, v9
	v_fmac_f32_e32 v10, v11, v8
	v_fma_f32 v7, -v7, v10, v9
	v_div_fmas_f32 v7, v7, v8, v10
	v_div_fixup_f32 v5, v7, v6, v5
	ds_write_b32 v2, v5 offset:18432
; DI void mod_unit(const Params& p, int l, int cgi, ldsp_t smem) {
;     ...
;     const int c4 = tid & 15, ks = tid >> 4;
;     f32x4 acc[5];
; #pragma unroll
;     for (int q = 0; q < 5; ++q) acc[q] = (f32x4){0.f, 0.f, 0.f, 0.f};
;     const float* wp = p.w_mod + ((size_t)l * 1024 + ks * 32) * 6144 + cgi * 64 + c4 * 4;
; #pragma unroll 8
;     for (int kk = 0; kk < 32; ++kk) {
;         const f32x4 w = *(const f32x4*)(wp + (size_t)kk * 6144);
;         const int k = ks * 32 + kk;
; #pragma unroll
;         for (int q = 0; q < 5; ++q) acc[q] += w * s[q * 1024 + k];
;     }
.LBB0_427:
	s_or_b64 exec, exec, s[4:5]
	s_mul_hi_i32 s4, s10, 0x2aaaaaab
	s_lshr_b32 s5, s4, 31
	s_ashr_i32 s4, s4, 4
	s_add_i32 s4, s4, s5
	s_mul_i32 s5, s4, 0x60
	v_ashrrev_i32_e32 v25, 4, v24
	s_sub_i32 s8, s10, s5
	s_ashr_i32 s5, s4, 31
	v_lshlrev_b32_e32 v0, 5, v25
	s_lshl_b64 s[6:7], s[4:5], 10
	v_ashrrev_i32_e32 v1, 31, v0
	v_lshl_add_u64 v[0:1], s[6:7], 0, v[0:1]
	s_waitcnt lgkmcnt(0)
	v_mov_b64_e32 v[4:5], s[20:21]
	v_mad_u64_u32 v[4:5], s[6:7], v0, s28, v[4:5]
	s_lshl_b32 s6, s8, 6
	v_mad_i32_i24 v5, v1, s28, v5
	s_ashr_i32 s7, s6, 31
	v_and_b32_e32 v30, 60, v2
	v_lshl_add_u64 v[0:1], s[6:7], 2, v[4:5]
	v_lshlrev_b32_e32 v192, 2, v30
	v_lshl_add_u64 v[26:27], v[0:1], 0, v[192:193]
	v_mov_b32_e32 v0, 0
	v_lshlrev_b32_e32 v31, 7, v25
	s_mov_b64 s[8:9], 0
	v_mov_b32_e32 v1, v0
	v_mov_b32_e32 v2, v0
	v_mov_b32_e32 v3, v0
	v_mov_b32_e32 v4, v0
	v_mov_b32_e32 v5, v0
	v_mov_b32_e32 v6, v0
	v_mov_b32_e32 v7, v0
	v_mov_b32_e32 v8, v0
	v_mov_b32_e32 v9, v0
	v_mov_b32_e32 v10, v0
	v_mov_b32_e32 v11, v0
	v_mov_b32_e32 v12, v0
	v_mov_b32_e32 v13, v0
	v_mov_b32_e32 v14, v0
	v_mov_b32_e32 v15, v0
	v_mov_b32_e32 v16, v0
	v_mov_b32_e32 v17, v0
	v_mov_b32_e32 v18, v0
	v_mov_b32_e32 v19, v0
	s_barrier
	v_lshl_add_u64 v[120:121], v[26:27], 0, s[8:9]
	global_load_dwordx4 v[56:59], v[120:121], off
	v_add_co_u32_e32 v122, vcc, s28, v120
	s_nop 1
	v_addc_co_u32_e32 v123, vcc, 0, v121, vcc
	global_load_dwordx4 v[60:63], v[122:123], off
	v_add_co_u32_e32 v122, vcc, 0xc000, v120
	s_nop 1
	v_addc_co_u32_e32 v123, vcc, 0, v121, vcc
	global_load_dwordx4 v[64:67], v[122:123], off
	v_add_co_u32_e32 v122, vcc, 0x12000, v120
	s_nop 1
	v_addc_co_u32_e32 v123, vcc, 0, v121, vcc
	global_load_dwordx4 v[68:71], v[122:123], off
	v_add_co_u32_e32 v122, vcc, s30, v120
	s_nop 1
	v_addc_co_u32_e32 v123, vcc, 0, v121, vcc
	global_load_dwordx4 v[72:75], v[122:123], off
	v_add_co_u32_e32 v122, vcc, 0x1e000, v120
	s_nop 1
	v_addc_co_u32_e32 v123, vcc, 0, v121, vcc
	global_load_dwordx4 v[76:79], v[122:123], off
	v_add_co_u32_e32 v122, vcc, 0x24000, v120
	s_nop 1
	v_addc_co_u32_e32 v123, vcc, 0, v121, vcc
	global_load_dwordx4 v[80:83], v[122:123], off
	v_add_co_u32_e32 v122, vcc, 0x2a000, v120
	s_nop 1
	v_addc_co_u32_e32 v123, vcc, 0, v121, vcc
	global_load_dwordx4 v[84:87], v[122:123], off
.LBB0_428:
	v_lshl_add_u64 v[28:29], v[26:27], 0, s[8:9]
	s_add_u32 s100, s8, 0x30000
	s_addc_u32 s101, s9, 0
	v_lshl_add_u64 v[120:121], v[26:27], 0, s[100:101]
	global_load_dwordx4 v[88:91], v[120:121], off
	v_add_co_u32_e32 v122, vcc, s28, v120
	s_nop 1
	v_addc_co_u32_e32 v123, vcc, 0, v121, vcc
	global_load_dwordx4 v[92:95], v[122:123], off
	v_add_co_u32_e32 v122, vcc, 0xc000, v120
	s_nop 1
	v_addc_co_u32_e32 v123, vcc, 0, v121, vcc
	global_load_dwordx4 v[96:99], v[122:123], off
	v_add_co_u32_e32 v122, vcc, 0x12000, v120
	s_nop 1
	v_addc_co_u32_e32 v123, vcc, 0, v121, vcc
	global_load_dwordx4 v[100:103], v[122:123], off
	v_add_co_u32_e32 v122, vcc, s30, v120
	s_nop 1
	v_addc_co_u32_e32 v123, vcc, 0, v121, vcc
	global_load_dwordx4 v[104:107], v[122:123], off
	v_add_co_u32_e32 v122, vcc, 0x1e000, v120
	s_nop 1
	v_addc_co_u32_e32 v123, vcc, 0, v121, vcc
	global_load_dwordx4 v[108:111], v[122:123], off
	v_add_co_u32_e32 v122, vcc, 0x24000, v120
	s_nop 1
	v_addc_co_u32_e32 v123, vcc, 0, v121, vcc
	global_load_dwordx4 v[112:115], v[122:123], off
	v_add_co_u32_e32 v122, vcc, 0x2a000, v120
	s_nop 1
	v_addc_co_u32_e32 v123, vcc, 0, v121, vcc
	global_load_dwordx4 v[116:119], v[122:123], off
	s_nop 0
	ds_read_b128 v[36:39], v31
	ds_read_b128 v[20:23], v31 offset:16
	s_mov_b32 s5, 0xc000
	s_add_u32 s8, s8, 0x30000
	s_addc_u32 s9, s9, 0
	s_cmp_eq_u32 s8, 0xc0000
	s_waitcnt vmcnt(15) lgkmcnt(1)
	v_mov_b64_e32 v[32:33], v[56:57]
	v_mov_b64_e32 v[34:35], v[58:59]
	v_pk_fma_f32 v[40:41], v[34:35], v[36:37], v[6:7] op_sel_hi:[1,0,1]
	v_pk_fma_f32 v[42:43], v[32:33], v[36:37], v[4:5] op_sel_hi:[1,0,1]
	ds_read_b128 v[4:7], v31 offset:4096
	s_waitcnt lgkmcnt(0)
	v_pk_fma_f32 v[44:45], v[34:35], v[4:5], v[10:11] op_sel_hi:[1,0,1]
	v_pk_fma_f32 v[46:47], v[32:33], v[4:5], v[8:9] op_sel_hi:[1,0,1]
	ds_read_b128 v[8:11], v31 offset:8192
	s_waitcnt lgkmcnt(0)
	v_pk_fma_f32 v[48:49], v[34:35], v[8:9], v[14:15] op_sel_hi:[1,0,1]
	v_pk_fma_f32 v[50:51], v[32:33], v[8:9], v[12:13] op_sel_hi:[1,0,1]
	ds_read_b128 v[12:15], v31 offset:12288
	s_waitcnt lgkmcnt(0)
	v_pk_fma_f32 v[52:53], v[34:35], v[12:13], v[18:19] op_sel_hi:[1,0,1]
	v_pk_fma_f32 v[54:55], v[32:33], v[12:13], v[16:17] op_sel_hi:[1,0,1]
	ds_read_b128 v[16:19], v31 offset:16384
	s_waitcnt lgkmcnt(0)
	v_pk_fma_f32 v[32:33], v[32:33], v[16:17], v[0:1] op_sel_hi:[1,0,1]
	v_add_co_u32_e32 v0, vcc, s28, v28
	v_pk_fma_f32 v[34:35], v[34:35], v[16:17], v[2:3] op_sel_hi:[1,0,1]
	s_nop 0
	v_addc_co_u32_e32 v1, vcc, 0, v29, vcc
	s_nop 0
	s_waitcnt vmcnt(14)
	v_mov_b64_e32 v[0:1], v[60:61]
	v_mov_b64_e32 v[2:3], v[62:63]
	v_pk_fma_f32 v[42:43], v[0:1], v[36:37], v[42:43] op_sel:[0,1,0]
	v_pk_fma_f32 v[36:37], v[2:3], v[36:37], v[40:41] op_sel:[0,1,0]
	v_pk_fma_f32 v[40:41], v[0:1], v[4:5], v[46:47] op_sel:[0,1,0]
	v_pk_fma_f32 v[4:5], v[2:3], v[4:5], v[44:45] op_sel:[0,1,0]
	v_pk_fma_f32 v[44:45], v[0:1], v[8:9], v[50:51] op_sel:[0,1,0]
	v_pk_fma_f32 v[46:47], v[0:1], v[12:13], v[54:55] op_sel:[0,1,0]
	v_pk_fma_f32 v[32:33], v[0:1], v[16:17], v[32:33] op_sel:[0,1,0]
	v_add_co_u32_e32 v0, vcc, s5, v28
	v_pk_fma_f32 v[8:9], v[2:3], v[8:9], v[48:49] op_sel:[0,1,0]
	s_nop 0
	v_addc_co_u32_e32 v1, vcc, 0, v29, vcc
	v_pk_fma_f32 v[12:13], v[2:3], v[12:13], v[52:53] op_sel:[0,1,0]
	v_pk_fma_f32 v[16:17], v[2:3], v[16:17], v[34:35] op_sel:[0,1,0]
	s_nop 0
	s_mov_b32 s5, 0x12000
	s_waitcnt vmcnt(13)
; DI void mod_unit(const Params& p, int l, int cgi, ldsp_t smem) {
;     ...
;     for (int kk = 0; kk < 32; ++kk) {
;         const f32x4 w = *(const f32x4*)(wp + (size_t)kk * 6144);
;         const int k = ks * 32 + kk;
; #pragma unroll
;         for (int q = 0; q < 5; ++q) acc[q] += w * s[q * 1024 + k];
;     }
	v_mov_b64_e32 v[0:1], v[64:65]
	v_mov_b64_e32 v[2:3], v[66:67]
	v_pk_fma_f32 v[34:35], v[2:3], v[38:39], v[36:37] op_sel_hi:[1,0,1]
	v_pk_fma_f32 v[36:37], v[0:1], v[38:39], v[42:43] op_sel_hi:[1,0,1]
	v_pk_fma_f32 v[40:41], v[0:1], v[6:7], v[40:41] op_sel_hi:[1,0,1]
	v_pk_fma_f32 v[42:43], v[0:1], v[10:11], v[44:45] op_sel_hi:[1,0,1]
	v_pk_fma_f32 v[44:45], v[0:1], v[14:15], v[46:47] op_sel_hi:[1,0,1]
	v_pk_fma_f32 v[32:33], v[0:1], v[18:19], v[32:33] op_sel_hi:[1,0,1]
	v_add_co_u32_e32 v0, vcc, s5, v28
	v_pk_fma_f32 v[4:5], v[2:3], v[6:7], v[4:5] op_sel_hi:[1,0,1]
	s_nop 0
	v_addc_co_u32_e32 v1, vcc, 0, v29, vcc
	v_pk_fma_f32 v[8:9], v[2:3], v[10:11], v[8:9] op_sel_hi:[1,0,1]
	v_pk_fma_f32 v[12:13], v[2:3], v[14:15], v[12:13] op_sel_hi:[1,0,1]
	v_pk_fma_f32 v[16:17], v[2:3], v[18:19], v[16:17] op_sel_hi:[1,0,1]
	s_nop 0
	v_mov_b32_e32 v6, v39
	s_mov_b32 s5, 0x1e000
	s_waitcnt vmcnt(12)
	v_mov_b64_e32 v[0:1], v[68:69]
	v_mov_b64_e32 v[2:3], v[70:71]
	v_pk_fma_f32 v[34:35], v[2:3], v[6:7], v[34:35] op_sel_hi:[1,0,1]
	v_pk_fma_f32 v[36:37], v[0:1], v[6:7], v[36:37] op_sel_hi:[1,0,1]
	v_mov_b32_e32 v6, v7
	v_pk_fma_f32 v[4:5], v[2:3], v[6:7], v[4:5] op_sel_hi:[1,0,1]
	v_pk_fma_f32 v[38:39], v[0:1], v[6:7], v[40:41] op_sel_hi:[1,0,1]
	v_mov_b32_e32 v6, v11
	v_pk_fma_f32 v[40:41], v[2:3], v[6:7], v[8:9] op_sel_hi:[1,0,1]
	v_pk_fma_f32 v[42:43], v[0:1], v[6:7], v[42:43] op_sel_hi:[1,0,1]
	v_mov_b32_e32 v6, v15
	v_pk_fma_f32 v[46:47], v[2:3], v[6:7], v[12:13] op_sel_hi:[1,0,1]
	v_pk_fma_f32 v[44:45], v[0:1], v[6:7], v[44:45] op_sel_hi:[1,0,1]
	v_mov_b32_e32 v6, v19
	v_pk_fma_f32 v[48:49], v[0:1], v[6:7], v[32:33] op_sel_hi:[1,0,1]
	v_add_co_u32_e32 v0, vcc, s30, v28
	v_pk_fma_f32 v[18:19], v[2:3], v[6:7], v[16:17] op_sel_hi:[1,0,1]
	s_nop 0
	v_addc_co_u32_e32 v1, vcc, 0, v29, vcc
	s_nop 0
	ds_read_b128 v[6:9], v31 offset:4112
	ds_read_b128 v[10:13], v31 offset:8208
	ds_read_b128 v[14:17], v31 offset:12304
	s_waitcnt vmcnt(11)
	v_mov_b64_e32 v[0:1], v[72:73]
	v_mov_b64_e32 v[2:3], v[74:75]
	v_pk_fma_f32 v[50:51], v[2:3], v[20:21], v[34:35] op_sel_hi:[1,0,1]
	ds_read_b128 v[32:35], v31 offset:16400
	v_pk_fma_f32 v[36:37], v[0:1], v[20:21], v[36:37] op_sel_hi:[1,0,1]
	s_waitcnt lgkmcnt(3)
	v_pk_fma_f32 v[38:39], v[0:1], v[6:7], v[38:39] op_sel_hi:[1,0,1]
	s_waitcnt lgkmcnt(2)
	v_pk_fma_f32 v[42:43], v[0:1], v[10:11], v[42:43] op_sel_hi:[1,0,1]
	s_waitcnt lgkmcnt(1)
	v_pk_fma_f32 v[44:45], v[0:1], v[14:15], v[44:45] op_sel_hi:[1,0,1]
	s_waitcnt lgkmcnt(0)
	v_pk_fma_f32 v[48:49], v[0:1], v[32:33], v[48:49] op_sel_hi:[1,0,1]
	v_add_co_u32_e32 v0, vcc, s5, v28
	v_pk_fma_f32 v[4:5], v[2:3], v[6:7], v[4:5] op_sel_hi:[1,0,1]
	s_nop 0
	v_addc_co_u32_e32 v1, vcc, 0, v29, vcc
	v_pk_fma_f32 v[40:41], v[2:3], v[10:11], v[40:41] op_sel_hi:[1,0,1]
	v_pk_fma_f32 v[46:47], v[2:3], v[14:15], v[46:47] op_sel_hi:[1,0,1]
	v_pk_fma_f32 v[18:19], v[2:3], v[32:33], v[18:19] op_sel_hi:[1,0,1]
	s_nop 0
	s_mov_b32 s5, 0x24000
	v_add_u32_e32 v31, 32, v31
	s_waitcnt vmcnt(10)
	v_mov_b64_e32 v[0:1], v[76:77]
	v_mov_b64_e32 v[2:3], v[78:79]
	v_pk_fma_f32 v[50:51], v[2:3], v[20:21], v[50:51] op_sel:[0,1,0]
	v_pk_fma_f32 v[20:21], v[0:1], v[20:21], v[36:37] op_sel:[0,1,0]
	v_pk_fma_f32 v[4:5], v[2:3], v[6:7], v[4:5] op_sel:[0,1,0]
	v_pk_fma_f32 v[6:7], v[0:1], v[6:7], v[38:39] op_sel:[0,1,0]
	v_pk_fma_f32 v[36:37], v[2:3], v[10:11], v[40:41] op_sel:[0,1,0]
	v_pk_fma_f32 v[10:11], v[0:1], v[10:11], v[42:43] op_sel:[0,1,0]
	v_pk_fma_f32 v[38:39], v[2:3], v[14:15], v[46:47] op_sel:[0,1,0]
	v_pk_fma_f32 v[14:15], v[0:1], v[14:15], v[44:45] op_sel:[0,1,0]
	v_pk_fma_f32 v[18:19], v[2:3], v[32:33], v[18:19] op_sel:[0,1,0]
	v_pk_fma_f32 v[32:33], v[0:1], v[32:33], v[48:49] op_sel:[0,1,0]
	v_add_co_u32_e32 v0, vcc, s5, v28
	s_mov_b32 s5, 0x2a000
	s_nop 0
	v_addc_co_u32_e32 v1, vcc, 0, v29, vcc
	s_nop 0
	s_waitcnt vmcnt(9)
	v_mov_b64_e32 v[0:1], v[80:81]
	v_mov_b64_e32 v[2:3], v[82:83]
	v_pk_fma_f32 v[20:21], v[0:1], v[22:23], v[20:21] op_sel_hi:[1,0,1]
	v_pk_fma_f32 v[44:45], v[0:1], v[8:9], v[6:7] op_sel_hi:[1,0,1]
	v_pk_fma_f32 v[46:47], v[0:1], v[12:13], v[10:11] op_sel_hi:[1,0,1]
	v_pk_fma_f32 v[48:49], v[0:1], v[16:17], v[14:15] op_sel_hi:[1,0,1]
	v_pk_fma_f32 v[32:33], v[0:1], v[34:35], v[32:33] op_sel_hi:[1,0,1]
	v_add_co_u32_e32 v0, vcc, s5, v28
	v_pk_fma_f32 v[40:41], v[2:3], v[22:23], v[50:51] op_sel_hi:[1,0,1]
	s_nop 0
	v_addc_co_u32_e32 v1, vcc, 0, v29, vcc
	v_pk_fma_f32 v[42:43], v[2:3], v[8:9], v[4:5] op_sel_hi:[1,0,1]
	v_pk_fma_f32 v[36:37], v[2:3], v[12:13], v[36:37] op_sel_hi:[1,0,1]
	v_pk_fma_f32 v[38:39], v[2:3], v[16:17], v[38:39] op_sel_hi:[1,0,1]
	v_pk_fma_f32 v[50:51], v[2:3], v[34:35], v[18:19] op_sel_hi:[1,0,1]
	s_nop 0
	v_mov_b32_e32 v4, v23
	v_mov_b32_e32 v8, v9
	v_mov_b32_e32 v12, v13
	v_mov_b32_e32 v16, v17
	s_waitcnt vmcnt(8)
; DI void mod_unit(const Params& p, int l, int cgi, ldsp_t smem) {
;     ...
;     for (int kk = 0; kk < 32; ++kk) {
;         const f32x4 w = *(const f32x4*)(wp + (size_t)kk * 6144);
;         const int k = ks * 32 + kk;
; #pragma unroll
;         for (int q = 0; q < 5; ++q) acc[q] += w * s[q * 1024 + k];
;     }
	v_mov_b64_e32 v[0:1], v[84:85]
	v_mov_b64_e32 v[2:3], v[86:87]
	v_pk_fma_f32 v[6:7], v[2:3], v[4:5], v[40:41] op_sel_hi:[1,0,1]
	v_pk_fma_f32 v[4:5], v[0:1], v[4:5], v[20:21] op_sel_hi:[1,0,1]
	v_mov_b32_e32 v20, v35
	v_pk_fma_f32 v[10:11], v[2:3], v[8:9], v[42:43] op_sel_hi:[1,0,1]
	v_pk_fma_f32 v[8:9], v[0:1], v[8:9], v[44:45] op_sel_hi:[1,0,1]
	v_pk_fma_f32 v[14:15], v[2:3], v[12:13], v[36:37] op_sel_hi:[1,0,1]
	v_pk_fma_f32 v[12:13], v[0:1], v[12:13], v[46:47] op_sel_hi:[1,0,1]
	v_pk_fma_f32 v[18:19], v[2:3], v[16:17], v[38:39] op_sel_hi:[1,0,1]
	v_pk_fma_f32 v[16:17], v[0:1], v[16:17], v[48:49] op_sel_hi:[1,0,1]
	v_pk_fma_f32 v[2:3], v[2:3], v[20:21], v[50:51] op_sel_hi:[1,0,1]
	v_pk_fma_f32 v[0:1], v[0:1], v[20:21], v[32:33] op_sel_hi:[1,0,1]
	v_lshl_add_u64 v[28:29], v[26:27], 0, s[8:9]
	s_add_u32 s100, s8, 0x30000
	s_addc_u32 s101, s9, 0
	v_lshl_add_u64 v[120:121], v[26:27], 0, s[100:101]
	global_load_dwordx4 v[56:59], v[120:121], off
	v_add_co_u32_e32 v122, vcc, s28, v120
	s_nop 1
	v_addc_co_u32_e32 v123, vcc, 0, v121, vcc
	global_load_dwordx4 v[60:63], v[122:123], off
	v_add_co_u32_e32 v122, vcc, 0xc000, v120
	s_nop 1
	v_addc_co_u32_e32 v123, vcc, 0, v121, vcc
	global_load_dwordx4 v[64:67], v[122:123], off
	v_add_co_u32_e32 v122, vcc, 0x12000, v120
	s_nop 1
	v_addc_co_u32_e32 v123, vcc, 0, v121, vcc
	global_load_dwordx4 v[68:71], v[122:123], off
	v_add_co_u32_e32 v122, vcc, s30, v120
	s_nop 1
	v_addc_co_u32_e32 v123, vcc, 0, v121, vcc
	global_load_dwordx4 v[72:75], v[122:123], off
	v_add_co_u32_e32 v122, vcc, 0x1e000, v120
	s_nop 1
	v_addc_co_u32_e32 v123, vcc, 0, v121, vcc
	global_load_dwordx4 v[76:79], v[122:123], off
	v_add_co_u32_e32 v122, vcc, 0x24000, v120
	s_nop 1
	v_addc_co_u32_e32 v123, vcc, 0, v121, vcc
	global_load_dwordx4 v[80:83], v[122:123], off
	v_add_co_u32_e32 v122, vcc, 0x2a000, v120
	s_nop 1
	v_addc_co_u32_e32 v123, vcc, 0, v121, vcc
	global_load_dwordx4 v[84:87], v[122:123], off
	s_nop 0
	ds_read_b128 v[36:39], v31
	ds_read_b128 v[20:23], v31 offset:16
	s_mov_b32 s5, 0xc000
	s_add_u32 s8, s8, 0x30000
	s_addc_u32 s9, s9, 0
	s_cmp_eq_u32 s8, 0xc0000
	s_waitcnt vmcnt(15) lgkmcnt(1)
	v_mov_b64_e32 v[32:33], v[88:89]
	v_mov_b64_e32 v[34:35], v[90:91]
	v_pk_fma_f32 v[40:41], v[34:35], v[36:37], v[6:7] op_sel_hi:[1,0,1]
	v_pk_fma_f32 v[42:43], v[32:33], v[36:37], v[4:5] op_sel_hi:[1,0,1]
	ds_read_b128 v[4:7], v31 offset:4096
	s_waitcnt lgkmcnt(0)
	v_pk_fma_f32 v[44:45], v[34:35], v[4:5], v[10:11] op_sel_hi:[1,0,1]
	v_pk_fma_f32 v[46:47], v[32:33], v[4:5], v[8:9] op_sel_hi:[1,0,1]
	ds_read_b128 v[8:11], v31 offset:8192
	s_waitcnt lgkmcnt(0)
	v_pk_fma_f32 v[48:49], v[34:35], v[8:9], v[14:15] op_sel_hi:[1,0,1]
	v_pk_fma_f32 v[50:51], v[32:33], v[8:9], v[12:13] op_sel_hi:[1,0,1]
	ds_read_b128 v[12:15], v31 offset:12288
	s_waitcnt lgkmcnt(0)
	v_pk_fma_f32 v[52:53], v[34:35], v[12:13], v[18:19] op_sel_hi:[1,0,1]
	v_pk_fma_f32 v[54:55], v[32:33], v[12:13], v[16:17] op_sel_hi:[1,0,1]
	ds_read_b128 v[16:19], v31 offset:16384
	s_waitcnt lgkmcnt(0)
	v_pk_fma_f32 v[32:33], v[32:33], v[16:17], v[0:1] op_sel_hi:[1,0,1]
	v_add_co_u32_e32 v0, vcc, s28, v28
	v_pk_fma_f32 v[34:35], v[34:35], v[16:17], v[2:3] op_sel_hi:[1,0,1]
	s_nop 0
	v_addc_co_u32_e32 v1, vcc, 0, v29, vcc
	s_nop 0
	s_waitcnt vmcnt(14)
	v_mov_b64_e32 v[0:1], v[92:93]
	v_mov_b64_e32 v[2:3], v[94:95]
	v_pk_fma_f32 v[42:43], v[0:1], v[36:37], v[42:43] op_sel:[0,1,0]
	v_pk_fma_f32 v[36:37], v[2:3], v[36:37], v[40:41] op_sel:[0,1,0]
	v_pk_fma_f32 v[40:41], v[0:1], v[4:5], v[46:47] op_sel:[0,1,0]
	v_pk_fma_f32 v[4:5], v[2:3], v[4:5], v[44:45] op_sel:[0,1,0]
	v_pk_fma_f32 v[44:45], v[0:1], v[8:9], v[50:51] op_sel:[0,1,0]
	v_pk_fma_f32 v[46:47], v[0:1], v[12:13], v[54:55] op_sel:[0,1,0]
	v_pk_fma_f32 v[32:33], v[0:1], v[16:17], v[32:33] op_sel:[0,1,0]
	v_add_co_u32_e32 v0, vcc, s5, v28
	v_pk_fma_f32 v[8:9], v[2:3], v[8:9], v[48:49] op_sel:[0,1,0]
	s_nop 0
	v_addc_co_u32_e32 v1, vcc, 0, v29, vcc
	v_pk_fma_f32 v[12:13], v[2:3], v[12:13], v[52:53] op_sel:[0,1,0]
	v_pk_fma_f32 v[16:17], v[2:3], v[16:17], v[34:35] op_sel:[0,1,0]
	s_nop 0
	s_mov_b32 s5, 0x12000
	s_waitcnt vmcnt(13)
	v_mov_b64_e32 v[0:1], v[96:97]
	v_mov_b64_e32 v[2:3], v[98:99]
	v_pk_fma_f32 v[34:35], v[2:3], v[38:39], v[36:37] op_sel_hi:[1,0,1]
	v_pk_fma_f32 v[36:37], v[0:1], v[38:39], v[42:43] op_sel_hi:[1,0,1]
	v_pk_fma_f32 v[40:41], v[0:1], v[6:7], v[40:41] op_sel_hi:[1,0,1]
	v_pk_fma_f32 v[42:43], v[0:1], v[10:11], v[44:45] op_sel_hi:[1,0,1]
	v_pk_fma_f32 v[44:45], v[0:1], v[14:15], v[46:47] op_sel_hi:[1,0,1]
	v_pk_fma_f32 v[32:33], v[0:1], v[18:19], v[32:33] op_sel_hi:[1,0,1]
	v_add_co_u32_e32 v0, vcc, s5, v28
	v_pk_fma_f32 v[4:5], v[2:3], v[6:7], v[4:5] op_sel_hi:[1,0,1]
	s_nop 0
	v_addc_co_u32_e32 v1, vcc, 0, v29, vcc
	v_pk_fma_f32 v[8:9], v[2:3], v[10:11], v[8:9] op_sel_hi:[1,0,1]
	v_pk_fma_f32 v[12:13], v[2:3], v[14:15], v[12:13] op_sel_hi:[1,0,1]
	v_pk_fma_f32 v[16:17], v[2:3], v[18:19], v[16:17] op_sel_hi:[1,0,1]
	s_nop 0
	v_mov_b32_e32 v6, v39
	s_mov_b32 s5, 0x1e000
	s_waitcnt vmcnt(12)
	v_mov_b64_e32 v[0:1], v[100:101]
	v_mov_b64_e32 v[2:3], v[102:103]
	v_pk_fma_f32 v[34:35], v[2:3], v[6:7], v[34:35] op_sel_hi:[1,0,1]
	v_pk_fma_f32 v[36:37], v[0:1], v[6:7], v[36:37] op_sel_hi:[1,0,1]
	v_mov_b32_e32 v6, v7
	v_pk_fma_f32 v[4:5], v[2:3], v[6:7], v[4:5] op_sel_hi:[1,0,1]
	v_pk_fma_f32 v[38:39], v[0:1], v[6:7], v[40:41] op_sel_hi:[1,0,1]
	v_mov_b32_e32 v6, v11
	v_pk_fma_f32 v[40:41], v[2:3], v[6:7], v[8:9] op_sel_hi:[1,0,1]
	v_pk_fma_f32 v[42:43], v[0:1], v[6:7], v[42:43] op_sel_hi:[1,0,1]
	v_mov_b32_e32 v6, v15
	v_pk_fma_f32 v[46:47], v[2:3], v[6:7], v[12:13] op_sel_hi:[1,0,1]
	v_pk_fma_f32 v[44:45], v[0:1], v[6:7], v[44:45] op_sel_hi:[1,0,1]
	v_mov_b32_e32 v6, v19
	v_pk_fma_f32 v[48:49], v[0:1], v[6:7], v[32:33] op_sel_hi:[1,0,1]
	v_add_co_u32_e32 v0, vcc, s30, v28
	v_pk_fma_f32 v[18:19], v[2:3], v[6:7], v[16:17] op_sel_hi:[1,0,1]
	s_nop 0
	v_addc_co_u32_e32 v1, vcc, 0, v29, vcc
	s_nop 0
	ds_read_b128 v[6:9], v31 offset:4112
	ds_read_b128 v[10:13], v31 offset:8208
	ds_read_b128 v[14:17], v31 offset:12304
	s_waitcnt vmcnt(11)
; DI void mod_unit(const Params& p, int l, int cgi, ldsp_t smem) {
;     ...
;     for (int kk = 0; kk < 32; ++kk) {
;         const f32x4 w = *(const f32x4*)(wp + (size_t)kk * 6144);
;         const int k = ks * 32 + kk;
; #pragma unroll
;         for (int q = 0; q < 5; ++q) acc[q] += w * s[q * 1024 + k];
;     }
	v_mov_b64_e32 v[0:1], v[104:105]
	v_mov_b64_e32 v[2:3], v[106:107]
	v_pk_fma_f32 v[50:51], v[2:3], v[20:21], v[34:35] op_sel_hi:[1,0,1]
	ds_read_b128 v[32:35], v31 offset:16400
	v_pk_fma_f32 v[36:37], v[0:1], v[20:21], v[36:37] op_sel_hi:[1,0,1]
	s_waitcnt lgkmcnt(3)
	v_pk_fma_f32 v[38:39], v[0:1], v[6:7], v[38:39] op_sel_hi:[1,0,1]
	s_waitcnt lgkmcnt(2)
	v_pk_fma_f32 v[42:43], v[0:1], v[10:11], v[42:43] op_sel_hi:[1,0,1]
	s_waitcnt lgkmcnt(1)
	v_pk_fma_f32 v[44:45], v[0:1], v[14:15], v[44:45] op_sel_hi:[1,0,1]
	s_waitcnt lgkmcnt(0)
	v_pk_fma_f32 v[48:49], v[0:1], v[32:33], v[48:49] op_sel_hi:[1,0,1]
	v_add_co_u32_e32 v0, vcc, s5, v28
	v_pk_fma_f32 v[4:5], v[2:3], v[6:7], v[4:5] op_sel_hi:[1,0,1]
	s_nop 0
	v_addc_co_u32_e32 v1, vcc, 0, v29, vcc
	v_pk_fma_f32 v[40:41], v[2:3], v[10:11], v[40:41] op_sel_hi:[1,0,1]
	v_pk_fma_f32 v[46:47], v[2:3], v[14:15], v[46:47] op_sel_hi:[1,0,1]
	v_pk_fma_f32 v[18:19], v[2:3], v[32:33], v[18:19] op_sel_hi:[1,0,1]
	s_nop 0
	s_mov_b32 s5, 0x24000
	v_add_u32_e32 v31, 32, v31
	s_waitcnt vmcnt(10)
	v_mov_b64_e32 v[0:1], v[108:109]
	v_mov_b64_e32 v[2:3], v[110:111]
	v_pk_fma_f32 v[50:51], v[2:3], v[20:21], v[50:51] op_sel:[0,1,0]
	v_pk_fma_f32 v[20:21], v[0:1], v[20:21], v[36:37] op_sel:[0,1,0]
	v_pk_fma_f32 v[4:5], v[2:3], v[6:7], v[4:5] op_sel:[0,1,0]
	v_pk_fma_f32 v[6:7], v[0:1], v[6:7], v[38:39] op_sel:[0,1,0]
	v_pk_fma_f32 v[36:37], v[2:3], v[10:11], v[40:41] op_sel:[0,1,0]
	v_pk_fma_f32 v[10:11], v[0:1], v[10:11], v[42:43] op_sel:[0,1,0]
	v_pk_fma_f32 v[38:39], v[2:3], v[14:15], v[46:47] op_sel:[0,1,0]
	v_pk_fma_f32 v[14:15], v[0:1], v[14:15], v[44:45] op_sel:[0,1,0]
	v_pk_fma_f32 v[18:19], v[2:3], v[32:33], v[18:19] op_sel:[0,1,0]
	v_pk_fma_f32 v[32:33], v[0:1], v[32:33], v[48:49] op_sel:[0,1,0]
	v_add_co_u32_e32 v0, vcc, s5, v28
	s_mov_b32 s5, 0x2a000
	s_nop 0
	v_addc_co_u32_e32 v1, vcc, 0, v29, vcc
	s_nop 0
	s_waitcnt vmcnt(9)
	v_mov_b64_e32 v[0:1], v[112:113]
	v_mov_b64_e32 v[2:3], v[114:115]
	v_pk_fma_f32 v[20:21], v[0:1], v[22:23], v[20:21] op_sel_hi:[1,0,1]
	v_pk_fma_f32 v[44:45], v[0:1], v[8:9], v[6:7] op_sel_hi:[1,0,1]
	v_pk_fma_f32 v[46:47], v[0:1], v[12:13], v[10:11] op_sel_hi:[1,0,1]
	v_pk_fma_f32 v[48:49], v[0:1], v[16:17], v[14:15] op_sel_hi:[1,0,1]
	v_pk_fma_f32 v[32:33], v[0:1], v[34:35], v[32:33] op_sel_hi:[1,0,1]
	v_add_co_u32_e32 v0, vcc, s5, v28
	v_pk_fma_f32 v[40:41], v[2:3], v[22:23], v[50:51] op_sel_hi:[1,0,1]
	s_nop 0
	v_addc_co_u32_e32 v1, vcc, 0, v29, vcc
	v_pk_fma_f32 v[42:43], v[2:3], v[8:9], v[4:5] op_sel_hi:[1,0,1]
	v_pk_fma_f32 v[36:37], v[2:3], v[12:13], v[36:37] op_sel_hi:[1,0,1]
	v_pk_fma_f32 v[38:39], v[2:3], v[16:17], v[38:39] op_sel_hi:[1,0,1]
	v_pk_fma_f32 v[50:51], v[2:3], v[34:35], v[18:19] op_sel_hi:[1,0,1]
	s_nop 0
	v_mov_b32_e32 v4, v23
	v_mov_b32_e32 v8, v9
	v_mov_b32_e32 v12, v13
	v_mov_b32_e32 v16, v17
	s_waitcnt vmcnt(8)
	v_mov_b64_e32 v[0:1], v[116:117]
	v_mov_b64_e32 v[2:3], v[118:119]
	v_pk_fma_f32 v[6:7], v[2:3], v[4:5], v[40:41] op_sel_hi:[1,0,1]
	v_pk_fma_f32 v[4:5], v[0:1], v[4:5], v[20:21] op_sel_hi:[1,0,1]
	v_mov_b32_e32 v20, v35
	v_pk_fma_f32 v[10:11], v[2:3], v[8:9], v[42:43] op_sel_hi:[1,0,1]
	v_pk_fma_f32 v[8:9], v[0:1], v[8:9], v[44:45] op_sel_hi:[1,0,1]
	v_pk_fma_f32 v[14:15], v[2:3], v[12:13], v[36:37] op_sel_hi:[1,0,1]
	v_pk_fma_f32 v[12:13], v[0:1], v[12:13], v[46:47] op_sel_hi:[1,0,1]
	v_pk_fma_f32 v[18:19], v[2:3], v[16:17], v[38:39] op_sel_hi:[1,0,1]
	v_pk_fma_f32 v[16:17], v[0:1], v[16:17], v[48:49] op_sel_hi:[1,0,1]
	v_pk_fma_f32 v[2:3], v[2:3], v[20:21], v[50:51] op_sel_hi:[1,0,1]
	v_pk_fma_f32 v[0:1], v[0:1], v[20:21], v[32:33] op_sel_hi:[1,0,1]
	v_lshl_add_u64 v[28:29], v[26:27], 0, s[8:9]
	s_add_u32 s100, s8, 0x30000
	s_addc_u32 s101, s9, 0
	v_lshl_add_u64 v[120:121], v[26:27], 0, s[100:101]
	global_load_dwordx4 v[88:91], v[120:121], off
	v_add_co_u32_e32 v122, vcc, s28, v120
	s_nop 1
	v_addc_co_u32_e32 v123, vcc, 0, v121, vcc
	global_load_dwordx4 v[92:95], v[122:123], off
	v_add_co_u32_e32 v122, vcc, 0xc000, v120
	s_nop 1
	v_addc_co_u32_e32 v123, vcc, 0, v121, vcc
	global_load_dwordx4 v[96:99], v[122:123], off
	v_add_co_u32_e32 v122, vcc, 0x12000, v120
	s_nop 1
	v_addc_co_u32_e32 v123, vcc, 0, v121, vcc
	global_load_dwordx4 v[100:103], v[122:123], off
	v_add_co_u32_e32 v122, vcc, s30, v120
	s_nop 1
	v_addc_co_u32_e32 v123, vcc, 0, v121, vcc
	global_load_dwordx4 v[104:107], v[122:123], off
	v_add_co_u32_e32 v122, vcc, 0x1e000, v120
	s_nop 1
	v_addc_co_u32_e32 v123, vcc, 0, v121, vcc
	global_load_dwordx4 v[108:111], v[122:123], off
	v_add_co_u32_e32 v122, vcc, 0x24000, v120
	s_nop 1
	v_addc_co_u32_e32 v123, vcc, 0, v121, vcc
	global_load_dwordx4 v[112:115], v[122:123], off
	v_add_co_u32_e32 v122, vcc, 0x2a000, v120
	s_nop 1
	v_addc_co_u32_e32 v123, vcc, 0, v121, vcc
	global_load_dwordx4 v[116:119], v[122:123], off
	s_nop 0
	ds_read_b128 v[36:39], v31
	ds_read_b128 v[20:23], v31 offset:16
	s_mov_b32 s5, 0xc000
	s_add_u32 s8, s8, 0x30000
	s_addc_u32 s9, s9, 0
	s_cmp_eq_u32 s8, 0xc0000
	s_waitcnt vmcnt(15) lgkmcnt(1)
	v_mov_b64_e32 v[32:33], v[56:57]
	v_mov_b64_e32 v[34:35], v[58:59]
	v_pk_fma_f32 v[40:41], v[34:35], v[36:37], v[6:7] op_sel_hi:[1,0,1]
	v_pk_fma_f32 v[42:43], v[32:33], v[36:37], v[4:5] op_sel_hi:[1,0,1]
	ds_read_b128 v[4:7], v31 offset:4096
	s_waitcnt lgkmcnt(0)
	v_pk_fma_f32 v[44:45], v[34:35], v[4:5], v[10:11] op_sel_hi:[1,0,1]
	v_pk_fma_f32 v[46:47], v[32:33], v[4:5], v[8:9] op_sel_hi:[1,0,1]
	ds_read_b128 v[8:11], v31 offset:8192
	s_waitcnt lgkmcnt(0)
	v_pk_fma_f32 v[48:49], v[34:35], v[8:9], v[14:15] op_sel_hi:[1,0,1]
	v_pk_fma_f32 v[50:51], v[32:33], v[8:9], v[12:13] op_sel_hi:[1,0,1]
	ds_read_b128 v[12:15], v31 offset:12288
	s_waitcnt lgkmcnt(0)
; DI void mod_unit(const Params& p, int l, int cgi, ldsp_t smem) {
;     ...
;     for (int kk = 0; kk < 32; ++kk) {
;         const f32x4 w = *(const f32x4*)(wp + (size_t)kk * 6144);
;         const int k = ks * 32 + kk;
; #pragma unroll
;         for (int q = 0; q < 5; ++q) acc[q] += w * s[q * 1024 + k];
;     }
	v_pk_fma_f32 v[52:53], v[34:35], v[12:13], v[18:19] op_sel_hi:[1,0,1]
	v_pk_fma_f32 v[54:55], v[32:33], v[12:13], v[16:17] op_sel_hi:[1,0,1]
	ds_read_b128 v[16:19], v31 offset:16384
	s_waitcnt lgkmcnt(0)
	v_pk_fma_f32 v[32:33], v[32:33], v[16:17], v[0:1] op_sel_hi:[1,0,1]
	v_add_co_u32_e32 v0, vcc, s28, v28
	v_pk_fma_f32 v[34:35], v[34:35], v[16:17], v[2:3] op_sel_hi:[1,0,1]
	s_nop 0
	v_addc_co_u32_e32 v1, vcc, 0, v29, vcc
	s_nop 0
	s_waitcnt vmcnt(14)
	v_mov_b64_e32 v[0:1], v[60:61]
	v_mov_b64_e32 v[2:3], v[62:63]
	v_pk_fma_f32 v[42:43], v[0:1], v[36:37], v[42:43] op_sel:[0,1,0]
	v_pk_fma_f32 v[36:37], v[2:3], v[36:37], v[40:41] op_sel:[0,1,0]
	v_pk_fma_f32 v[40:41], v[0:1], v[4:5], v[46:47] op_sel:[0,1,0]
	v_pk_fma_f32 v[4:5], v[2:3], v[4:5], v[44:45] op_sel:[0,1,0]
	v_pk_fma_f32 v[44:45], v[0:1], v[8:9], v[50:51] op_sel:[0,1,0]
	v_pk_fma_f32 v[46:47], v[0:1], v[12:13], v[54:55] op_sel:[0,1,0]
	v_pk_fma_f32 v[32:33], v[0:1], v[16:17], v[32:33] op_sel:[0,1,0]
	v_add_co_u32_e32 v0, vcc, s5, v28
	v_pk_fma_f32 v[8:9], v[2:3], v[8:9], v[48:49] op_sel:[0,1,0]
	s_nop 0
	v_addc_co_u32_e32 v1, vcc, 0, v29, vcc
	v_pk_fma_f32 v[12:13], v[2:3], v[12:13], v[52:53] op_sel:[0,1,0]
	v_pk_fma_f32 v[16:17], v[2:3], v[16:17], v[34:35] op_sel:[0,1,0]
	s_nop 0
	s_mov_b32 s5, 0x12000
	s_waitcnt vmcnt(13)
	v_mov_b64_e32 v[0:1], v[64:65]
	v_mov_b64_e32 v[2:3], v[66:67]
	v_pk_fma_f32 v[34:35], v[2:3], v[38:39], v[36:37] op_sel_hi:[1,0,1]
	v_pk_fma_f32 v[36:37], v[0:1], v[38:39], v[42:43] op_sel_hi:[1,0,1]
	v_pk_fma_f32 v[40:41], v[0:1], v[6:7], v[40:41] op_sel_hi:[1,0,1]
	v_pk_fma_f32 v[42:43], v[0:1], v[10:11], v[44:45] op_sel_hi:[1,0,1]
	v_pk_fma_f32 v[44:45], v[0:1], v[14:15], v[46:47] op_sel_hi:[1,0,1]
	v_pk_fma_f32 v[32:33], v[0:1], v[18:19], v[32:33] op_sel_hi:[1,0,1]
	v_add_co_u32_e32 v0, vcc, s5, v28
	v_pk_fma_f32 v[4:5], v[2:3], v[6:7], v[4:5] op_sel_hi:[1,0,1]
	s_nop 0
	v_addc_co_u32_e32 v1, vcc, 0, v29, vcc
	v_pk_fma_f32 v[8:9], v[2:3], v[10:11], v[8:9] op_sel_hi:[1,0,1]
	v_pk_fma_f32 v[12:13], v[2:3], v[14:15], v[12:13] op_sel_hi:[1,0,1]
	v_pk_fma_f32 v[16:17], v[2:3], v[18:19], v[16:17] op_sel_hi:[1,0,1]
	s_nop 0
	v_mov_b32_e32 v6, v39
	s_mov_b32 s5, 0x1e000
	s_waitcnt vmcnt(12)
	v_mov_b64_e32 v[0:1], v[68:69]
	v_mov_b64_e32 v[2:3], v[70:71]
	v_pk_fma_f32 v[34:35], v[2:3], v[6:7], v[34:35] op_sel_hi:[1,0,1]
	v_pk_fma_f32 v[36:37], v[0:1], v[6:7], v[36:37] op_sel_hi:[1,0,1]
	v_mov_b32_e32 v6, v7
	v_pk_fma_f32 v[4:5], v[2:3], v[6:7], v[4:5] op_sel_hi:[1,0,1]
	v_pk_fma_f32 v[38:39], v[0:1], v[6:7], v[40:41] op_sel_hi:[1,0,1]
	v_mov_b32_e32 v6, v11
	v_pk_fma_f32 v[40:41], v[2:3], v[6:7], v[8:9] op_sel_hi:[1,0,1]
	v_pk_fma_f32 v[42:43], v[0:1], v[6:7], v[42:43] op_sel_hi:[1,0,1]
	v_mov_b32_e32 v6, v15
	v_pk_fma_f32 v[46:47], v[2:3], v[6:7], v[12:13] op_sel_hi:[1,0,1]
	v_pk_fma_f32 v[44:45], v[0:1], v[6:7], v[44:45] op_sel_hi:[1,0,1]
	v_mov_b32_e32 v6, v19
	v_pk_fma_f32 v[48:49], v[0:1], v[6:7], v[32:33] op_sel_hi:[1,0,1]
	v_add_co_u32_e32 v0, vcc, s30, v28
	v_pk_fma_f32 v[18:19], v[2:3], v[6:7], v[16:17] op_sel_hi:[1,0,1]
	s_nop 0
	v_addc_co_u32_e32 v1, vcc, 0, v29, vcc
	s_nop 0
	ds_read_b128 v[6:9], v31 offset:4112
	ds_read_b128 v[10:13], v31 offset:8208
	ds_read_b128 v[14:17], v31 offset:12304
	s_waitcnt vmcnt(11)
	v_mov_b64_e32 v[0:1], v[72:73]
	v_mov_b64_e32 v[2:3], v[74:75]
	v_pk_fma_f32 v[50:51], v[2:3], v[20:21], v[34:35] op_sel_hi:[1,0,1]
	ds_read_b128 v[32:35], v31 offset:16400
	v_pk_fma_f32 v[36:37], v[0:1], v[20:21], v[36:37] op_sel_hi:[1,0,1]
	s_waitcnt lgkmcnt(3)
	v_pk_fma_f32 v[38:39], v[0:1], v[6:7], v[38:39] op_sel_hi:[1,0,1]
	s_waitcnt lgkmcnt(2)
	v_pk_fma_f32 v[42:43], v[0:1], v[10:11], v[42:43] op_sel_hi:[1,0,1]
	s_waitcnt lgkmcnt(1)
	v_pk_fma_f32 v[44:45], v[0:1], v[14:15], v[44:45] op_sel_hi:[1,0,1]
	s_waitcnt lgkmcnt(0)
	v_pk_fma_f32 v[48:49], v[0:1], v[32:33], v[48:49] op_sel_hi:[1,0,1]
	v_add_co_u32_e32 v0, vcc, s5, v28
	v_pk_fma_f32 v[4:5], v[2:3], v[6:7], v[4:5] op_sel_hi:[1,0,1]
	s_nop 0
	v_addc_co_u32_e32 v1, vcc, 0, v29, vcc
	v_pk_fma_f32 v[40:41], v[2:3], v[10:11], v[40:41] op_sel_hi:[1,0,1]
	v_pk_fma_f32 v[46:47], v[2:3], v[14:15], v[46:47] op_sel_hi:[1,0,1]
	v_pk_fma_f32 v[18:19], v[2:3], v[32:33], v[18:19] op_sel_hi:[1,0,1]
	s_nop 0
	s_mov_b32 s5, 0x24000
	v_add_u32_e32 v31, 32, v31
	s_waitcnt vmcnt(10)
	v_mov_b64_e32 v[0:1], v[76:77]
	v_mov_b64_e32 v[2:3], v[78:79]
	v_pk_fma_f32 v[50:51], v[2:3], v[20:21], v[50:51] op_sel:[0,1,0]
	v_pk_fma_f32 v[20:21], v[0:1], v[20:21], v[36:37] op_sel:[0,1,0]
	v_pk_fma_f32 v[4:5], v[2:3], v[6:7], v[4:5] op_sel:[0,1,0]
	v_pk_fma_f32 v[6:7], v[0:1], v[6:7], v[38:39] op_sel:[0,1,0]
	v_pk_fma_f32 v[36:37], v[2:3], v[10:11], v[40:41] op_sel:[0,1,0]
	v_pk_fma_f32 v[10:11], v[0:1], v[10:11], v[42:43] op_sel:[0,1,0]
	v_pk_fma_f32 v[38:39], v[2:3], v[14:15], v[46:47] op_sel:[0,1,0]
	v_pk_fma_f32 v[14:15], v[0:1], v[14:15], v[44:45] op_sel:[0,1,0]
	v_pk_fma_f32 v[18:19], v[2:3], v[32:33], v[18:19] op_sel:[0,1,0]
	v_pk_fma_f32 v[32:33], v[0:1], v[32:33], v[48:49] op_sel:[0,1,0]
	v_add_co_u32_e32 v0, vcc, s5, v28
	s_mov_b32 s5, 0x2a000
	s_nop 0
	v_addc_co_u32_e32 v1, vcc, 0, v29, vcc
	s_nop 0
	s_waitcnt vmcnt(9)
	v_mov_b64_e32 v[0:1], v[80:81]
	v_mov_b64_e32 v[2:3], v[82:83]
	v_pk_fma_f32 v[20:21], v[0:1], v[22:23], v[20:21] op_sel_hi:[1,0,1]
	v_pk_fma_f32 v[44:45], v[0:1], v[8:9], v[6:7] op_sel_hi:[1,0,1]
	v_pk_fma_f32 v[46:47], v[0:1], v[12:13], v[10:11] op_sel_hi:[1,0,1]
	v_pk_fma_f32 v[48:49], v[0:1], v[16:17], v[14:15] op_sel_hi:[1,0,1]
	v_pk_fma_f32 v[32:33], v[0:1], v[34:35], v[32:33] op_sel_hi:[1,0,1]
	v_add_co_u32_e32 v0, vcc, s5, v28
	v_pk_fma_f32 v[40:41], v[2:3], v[22:23], v[50:51] op_sel_hi:[1,0,1]
	s_nop 0
	v_addc_co_u32_e32 v1, vcc, 0, v29, vcc
	v_pk_fma_f32 v[42:43], v[2:3], v[8:9], v[4:5] op_sel_hi:[1,0,1]
	v_pk_fma_f32 v[36:37], v[2:3], v[12:13], v[36:37] op_sel_hi:[1,0,1]
	v_pk_fma_f32 v[38:39], v[2:3], v[16:17], v[38:39] op_sel_hi:[1,0,1]
	v_pk_fma_f32 v[50:51], v[2:3], v[34:35], v[18:19] op_sel_hi:[1,0,1]
	s_nop 0
	v_mov_b32_e32 v4, v23
	v_mov_b32_e32 v8, v9
	v_mov_b32_e32 v12, v13
	v_mov_b32_e32 v16, v17
	s_waitcnt vmcnt(8)
; DI void mod_unit(const Params& p, int l, int cgi, ldsp_t smem) {
;     ...
;     for (int kk = 0; kk < 32; ++kk) {
;         const f32x4 w = *(const f32x4*)(wp + (size_t)kk * 6144);
;         const int k = ks * 32 + kk;
; #pragma unroll
;         for (int q = 0; q < 5; ++q) acc[q] += w * s[q * 1024 + k];
;     }
	v_mov_b64_e32 v[0:1], v[84:85]
	v_mov_b64_e32 v[2:3], v[86:87]
	v_pk_fma_f32 v[6:7], v[2:3], v[4:5], v[40:41] op_sel_hi:[1,0,1]
	v_pk_fma_f32 v[4:5], v[0:1], v[4:5], v[20:21] op_sel_hi:[1,0,1]
	v_mov_b32_e32 v20, v35
	v_pk_fma_f32 v[10:11], v[2:3], v[8:9], v[42:43] op_sel_hi:[1,0,1]
	v_pk_fma_f32 v[8:9], v[0:1], v[8:9], v[44:45] op_sel_hi:[1,0,1]
	v_pk_fma_f32 v[14:15], v[2:3], v[12:13], v[36:37] op_sel_hi:[1,0,1]
	v_pk_fma_f32 v[12:13], v[0:1], v[12:13], v[46:47] op_sel_hi:[1,0,1]
	v_pk_fma_f32 v[18:19], v[2:3], v[16:17], v[38:39] op_sel_hi:[1,0,1]
	v_pk_fma_f32 v[16:17], v[0:1], v[16:17], v[48:49] op_sel_hi:[1,0,1]
	v_pk_fma_f32 v[2:3], v[2:3], v[20:21], v[50:51] op_sel_hi:[1,0,1]
	v_pk_fma_f32 v[0:1], v[0:1], v[20:21], v[32:33] op_sel_hi:[1,0,1]
	v_lshl_add_u64 v[28:29], v[26:27], 0, s[8:9]
	s_nop 0
	ds_read_b128 v[36:39], v31
	ds_read_b128 v[20:23], v31 offset:16
	s_mov_b32 s5, 0xc000
	s_add_u32 s8, s8, 0x30000
	s_addc_u32 s9, s9, 0
	s_cmp_eq_u32 s8, 0xc0000
	s_waitcnt vmcnt(7) lgkmcnt(1)
	v_mov_b64_e32 v[32:33], v[88:89]
	v_mov_b64_e32 v[34:35], v[90:91]
	v_pk_fma_f32 v[40:41], v[34:35], v[36:37], v[6:7] op_sel_hi:[1,0,1]
	v_pk_fma_f32 v[42:43], v[32:33], v[36:37], v[4:5] op_sel_hi:[1,0,1]
	ds_read_b128 v[4:7], v31 offset:4096
	s_waitcnt lgkmcnt(0)
	v_pk_fma_f32 v[44:45], v[34:35], v[4:5], v[10:11] op_sel_hi:[1,0,1]
	v_pk_fma_f32 v[46:47], v[32:33], v[4:5], v[8:9] op_sel_hi:[1,0,1]
	ds_read_b128 v[8:11], v31 offset:8192
	s_waitcnt lgkmcnt(0)
	v_pk_fma_f32 v[48:49], v[34:35], v[8:9], v[14:15] op_sel_hi:[1,0,1]
	v_pk_fma_f32 v[50:51], v[32:33], v[8:9], v[12:13] op_sel_hi:[1,0,1]
	ds_read_b128 v[12:15], v31 offset:12288
	s_waitcnt lgkmcnt(0)
	v_pk_fma_f32 v[52:53], v[34:35], v[12:13], v[18:19] op_sel_hi:[1,0,1]
	v_pk_fma_f32 v[54:55], v[32:33], v[12:13], v[16:17] op_sel_hi:[1,0,1]
	ds_read_b128 v[16:19], v31 offset:16384
	s_waitcnt lgkmcnt(0)
	v_pk_fma_f32 v[32:33], v[32:33], v[16:17], v[0:1] op_sel_hi:[1,0,1]
	v_add_co_u32_e32 v0, vcc, s28, v28
	v_pk_fma_f32 v[34:35], v[34:35], v[16:17], v[2:3] op_sel_hi:[1,0,1]
	s_nop 0
	v_addc_co_u32_e32 v1, vcc, 0, v29, vcc
	s_nop 0
	s_waitcnt vmcnt(6)
	v_mov_b64_e32 v[0:1], v[92:93]
	v_mov_b64_e32 v[2:3], v[94:95]
	v_pk_fma_f32 v[42:43], v[0:1], v[36:37], v[42:43] op_sel:[0,1,0]
	v_pk_fma_f32 v[36:37], v[2:3], v[36:37], v[40:41] op_sel:[0,1,0]
	v_pk_fma_f32 v[40:41], v[0:1], v[4:5], v[46:47] op_sel:[0,1,0]
	v_pk_fma_f32 v[4:5], v[2:3], v[4:5], v[44:45] op_sel:[0,1,0]
	v_pk_fma_f32 v[44:45], v[0:1], v[8:9], v[50:51] op_sel:[0,1,0]
	v_pk_fma_f32 v[46:47], v[0:1], v[12:13], v[54:55] op_sel:[0,1,0]
	v_pk_fma_f32 v[32:33], v[0:1], v[16:17], v[32:33] op_sel:[0,1,0]
	v_add_co_u32_e32 v0, vcc, s5, v28
	v_pk_fma_f32 v[8:9], v[2:3], v[8:9], v[48:49] op_sel:[0,1,0]
	s_nop 0
	v_addc_co_u32_e32 v1, vcc, 0, v29, vcc
	v_pk_fma_f32 v[12:13], v[2:3], v[12:13], v[52:53] op_sel:[0,1,0]
	v_pk_fma_f32 v[16:17], v[2:3], v[16:17], v[34:35] op_sel:[0,1,0]
	s_nop 0
	s_mov_b32 s5, 0x12000
	s_waitcnt vmcnt(5)
	v_mov_b64_e32 v[0:1], v[96:97]
	v_mov_b64_e32 v[2:3], v[98:99]
	v_pk_fma_f32 v[34:35], v[2:3], v[38:39], v[36:37] op_sel_hi:[1,0,1]
	v_pk_fma_f32 v[36:37], v[0:1], v[38:39], v[42:43] op_sel_hi:[1,0,1]
	v_pk_fma_f32 v[40:41], v[0:1], v[6:7], v[40:41] op_sel_hi:[1,0,1]
	v_pk_fma_f32 v[42:43], v[0:1], v[10:11], v[44:45] op_sel_hi:[1,0,1]
	v_pk_fma_f32 v[44:45], v[0:1], v[14:15], v[46:47] op_sel_hi:[1,0,1]
	v_pk_fma_f32 v[32:33], v[0:1], v[18:19], v[32:33] op_sel_hi:[1,0,1]
	v_add_co_u32_e32 v0, vcc, s5, v28
	v_pk_fma_f32 v[4:5], v[2:3], v[6:7], v[4:5] op_sel_hi:[1,0,1]
	s_nop 0
	v_addc_co_u32_e32 v1, vcc, 0, v29, vcc
	v_pk_fma_f32 v[8:9], v[2:3], v[10:11], v[8:9] op_sel_hi:[1,0,1]
	v_pk_fma_f32 v[12:13], v[2:3], v[14:15], v[12:13] op_sel_hi:[1,0,1]
	v_pk_fma_f32 v[16:17], v[2:3], v[18:19], v[16:17] op_sel_hi:[1,0,1]
	s_nop 0
	v_mov_b32_e32 v6, v39
	s_mov_b32 s5, 0x1e000
	s_waitcnt vmcnt(4)
	v_mov_b64_e32 v[0:1], v[100:101]
	v_mov_b64_e32 v[2:3], v[102:103]
	v_pk_fma_f32 v[34:35], v[2:3], v[6:7], v[34:35] op_sel_hi:[1,0,1]
	v_pk_fma_f32 v[36:37], v[0:1], v[6:7], v[36:37] op_sel_hi:[1,0,1]
	v_mov_b32_e32 v6, v7
	v_pk_fma_f32 v[4:5], v[2:3], v[6:7], v[4:5] op_sel_hi:[1,0,1]
	v_pk_fma_f32 v[38:39], v[0:1], v[6:7], v[40:41] op_sel_hi:[1,0,1]
	v_mov_b32_e32 v6, v11
	v_pk_fma_f32 v[40:41], v[2:3], v[6:7], v[8:9] op_sel_hi:[1,0,1]
	v_pk_fma_f32 v[42:43], v[0:1], v[6:7], v[42:43] op_sel_hi:[1,0,1]
	v_mov_b32_e32 v6, v15
	v_pk_fma_f32 v[46:47], v[2:3], v[6:7], v[12:13] op_sel_hi:[1,0,1]
	v_pk_fma_f32 v[44:45], v[0:1], v[6:7], v[44:45] op_sel_hi:[1,0,1]
	v_mov_b32_e32 v6, v19
	v_pk_fma_f32 v[48:49], v[0:1], v[6:7], v[32:33] op_sel_hi:[1,0,1]
	v_add_co_u32_e32 v0, vcc, s30, v28
	v_pk_fma_f32 v[18:19], v[2:3], v[6:7], v[16:17] op_sel_hi:[1,0,1]
	s_nop 0
	v_addc_co_u32_e32 v1, vcc, 0, v29, vcc
	s_nop 0
	ds_read_b128 v[6:9], v31 offset:4112
	ds_read_b128 v[10:13], v31 offset:8208
	ds_read_b128 v[14:17], v31 offset:12304
	s_waitcnt vmcnt(3)
	v_mov_b64_e32 v[0:1], v[104:105]
	v_mov_b64_e32 v[2:3], v[106:107]
	v_pk_fma_f32 v[50:51], v[2:3], v[20:21], v[34:35] op_sel_hi:[1,0,1]
	ds_read_b128 v[32:35], v31 offset:16400
	v_pk_fma_f32 v[36:37], v[0:1], v[20:21], v[36:37] op_sel_hi:[1,0,1]
	s_waitcnt lgkmcnt(3)
	v_pk_fma_f32 v[38:39], v[0:1], v[6:7], v[38:39] op_sel_hi:[1,0,1]
	s_waitcnt lgkmcnt(2)
	v_pk_fma_f32 v[42:43], v[0:1], v[10:11], v[42:43] op_sel_hi:[1,0,1]
	s_waitcnt lgkmcnt(1)
	v_pk_fma_f32 v[44:45], v[0:1], v[14:15], v[44:45] op_sel_hi:[1,0,1]
	s_waitcnt lgkmcnt(0)
; DI void mod_unit(const Params& p, int l, int cgi, ldsp_t smem) {
;     ...
;     for (int kk = 0; kk < 32; ++kk) {
;         const f32x4 w = *(const f32x4*)(wp + (size_t)kk * 6144);
;         const int k = ks * 32 + kk;
; #pragma unroll
;         for (int q = 0; q < 5; ++q) acc[q] += w * s[q * 1024 + k];
;     }
; #pragma unroll
;     for (int q = 0; q < 5; ++q)
; #pragma unroll
;         for (int j = 0; j < 4; ++j) red[(ks * 5 + q) * 64 + c4 * 4 + j] = acc[q][j];
;     __syncthreads();
;     if (tid < 320) {
;         const int q = tid >> 6, col = tid & 63;
;         float a = 0.f;
;         for (int k2 = 0; k2 < 32; ++k2) a += red[(k2 * 5 + q) * 64 + col];
;         const int j = cgi * 64 + col;
;         p.mod[((size_t)l * 5 + q) * 6144 + j] = a + p.b_mod[(size_t)l * 6144 + j];
;     }
	v_pk_fma_f32 v[48:49], v[0:1], v[32:33], v[48:49] op_sel_hi:[1,0,1]
	v_add_co_u32_e32 v0, vcc, s5, v28
	v_pk_fma_f32 v[4:5], v[2:3], v[6:7], v[4:5] op_sel_hi:[1,0,1]
	s_nop 0
	v_addc_co_u32_e32 v1, vcc, 0, v29, vcc
	v_pk_fma_f32 v[40:41], v[2:3], v[10:11], v[40:41] op_sel_hi:[1,0,1]
	v_pk_fma_f32 v[46:47], v[2:3], v[14:15], v[46:47] op_sel_hi:[1,0,1]
	v_pk_fma_f32 v[18:19], v[2:3], v[32:33], v[18:19] op_sel_hi:[1,0,1]
	s_nop 0
	s_mov_b32 s5, 0x24000
	v_add_u32_e32 v31, 32, v31
	s_waitcnt vmcnt(2)
	v_mov_b64_e32 v[0:1], v[108:109]
	v_mov_b64_e32 v[2:3], v[110:111]
	v_pk_fma_f32 v[50:51], v[2:3], v[20:21], v[50:51] op_sel:[0,1,0]
	v_pk_fma_f32 v[20:21], v[0:1], v[20:21], v[36:37] op_sel:[0,1,0]
	v_pk_fma_f32 v[4:5], v[2:3], v[6:7], v[4:5] op_sel:[0,1,0]
	v_pk_fma_f32 v[6:7], v[0:1], v[6:7], v[38:39] op_sel:[0,1,0]
	v_pk_fma_f32 v[36:37], v[2:3], v[10:11], v[40:41] op_sel:[0,1,0]
	v_pk_fma_f32 v[10:11], v[0:1], v[10:11], v[42:43] op_sel:[0,1,0]
	v_pk_fma_f32 v[38:39], v[2:3], v[14:15], v[46:47] op_sel:[0,1,0]
	v_pk_fma_f32 v[14:15], v[0:1], v[14:15], v[44:45] op_sel:[0,1,0]
	v_pk_fma_f32 v[18:19], v[2:3], v[32:33], v[18:19] op_sel:[0,1,0]
	v_pk_fma_f32 v[32:33], v[0:1], v[32:33], v[48:49] op_sel:[0,1,0]
	v_add_co_u32_e32 v0, vcc, s5, v28
	s_mov_b32 s5, 0x2a000
	s_nop 0
	v_addc_co_u32_e32 v1, vcc, 0, v29, vcc
	s_nop 0
	s_waitcnt vmcnt(1)
	v_mov_b64_e32 v[0:1], v[112:113]
	v_mov_b64_e32 v[2:3], v[114:115]
	v_pk_fma_f32 v[20:21], v[0:1], v[22:23], v[20:21] op_sel_hi:[1,0,1]
	v_pk_fma_f32 v[44:45], v[0:1], v[8:9], v[6:7] op_sel_hi:[1,0,1]
	v_pk_fma_f32 v[46:47], v[0:1], v[12:13], v[10:11] op_sel_hi:[1,0,1]
	v_pk_fma_f32 v[48:49], v[0:1], v[16:17], v[14:15] op_sel_hi:[1,0,1]
	v_pk_fma_f32 v[32:33], v[0:1], v[34:35], v[32:33] op_sel_hi:[1,0,1]
	v_add_co_u32_e32 v0, vcc, s5, v28
	v_pk_fma_f32 v[40:41], v[2:3], v[22:23], v[50:51] op_sel_hi:[1,0,1]
	s_nop 0
	v_addc_co_u32_e32 v1, vcc, 0, v29, vcc
	v_pk_fma_f32 v[42:43], v[2:3], v[8:9], v[4:5] op_sel_hi:[1,0,1]
	v_pk_fma_f32 v[36:37], v[2:3], v[12:13], v[36:37] op_sel_hi:[1,0,1]
	v_pk_fma_f32 v[38:39], v[2:3], v[16:17], v[38:39] op_sel_hi:[1,0,1]
	v_pk_fma_f32 v[50:51], v[2:3], v[34:35], v[18:19] op_sel_hi:[1,0,1]
	s_nop 0
	v_mov_b32_e32 v4, v23
	v_mov_b32_e32 v8, v9
	v_mov_b32_e32 v12, v13
	v_mov_b32_e32 v16, v17
	s_waitcnt vmcnt(0)
	v_mov_b64_e32 v[0:1], v[116:117]
	v_mov_b64_e32 v[2:3], v[118:119]
	v_pk_fma_f32 v[6:7], v[2:3], v[4:5], v[40:41] op_sel_hi:[1,0,1]
	v_pk_fma_f32 v[4:5], v[0:1], v[4:5], v[20:21] op_sel_hi:[1,0,1]
	v_mov_b32_e32 v20, v35
	v_pk_fma_f32 v[10:11], v[2:3], v[8:9], v[42:43] op_sel_hi:[1,0,1]
	v_pk_fma_f32 v[8:9], v[0:1], v[8:9], v[44:45] op_sel_hi:[1,0,1]
	v_pk_fma_f32 v[14:15], v[2:3], v[12:13], v[36:37] op_sel_hi:[1,0,1]
	v_pk_fma_f32 v[12:13], v[0:1], v[12:13], v[46:47] op_sel_hi:[1,0,1]
	v_pk_fma_f32 v[18:19], v[2:3], v[16:17], v[38:39] op_sel_hi:[1,0,1]
	v_pk_fma_f32 v[16:17], v[0:1], v[16:17], v[48:49] op_sel_hi:[1,0,1]
	v_pk_fma_f32 v[2:3], v[2:3], v[20:21], v[50:51] op_sel_hi:[1,0,1]
	v_pk_fma_f32 v[0:1], v[0:1], v[20:21], v[32:33] op_sel_hi:[1,0,1]
	s_movk_i32 s5, 0x500
	v_mul_lo_u32 v20, v25, s5
	s_movk_i32 s5, 0x140
	v_lshl_or_b32 v20, v30, 2, v20
	v_cmp_gt_i32_e32 vcc, s5, v24
	ds_write_b128 v20, v[4:7] offset:20480
	ds_write_b128 v20, v[8:11] offset:20736
	ds_write_b128 v20, v[12:15] offset:20992
	ds_write_b128 v20, v[16:19] offset:21248
	ds_write_b128 v20, v[0:3] offset:21504
	s_waitcnt lgkmcnt(0)
	s_barrier
	s_and_saveexec_b64 s[8:9], vcc
	s_cbranch_execz .LBB0_388
	v_ashrrev_i32_e32 v0, 6, v24
	v_and_b32_e32 v1, 63, v24
	v_lshlrev_b32_e32 v2, 8, v0
	v_lshl_or_b32 v4, v1, 2, v2
	ds_read2st64_b32 v[2:3], v4 offset0:80 offset1:85
	s_mul_hi_i32 s5, s4, 0x6000
	s_waitcnt lgkmcnt(0)
	v_add_f32_e32 v2, 0, v2
	v_add_f32_e32 v5, v2, v3
	ds_read2st64_b32 v[2:3], v4 offset0:90 offset1:95
	s_waitcnt lgkmcnt(0)
	v_add_f32_e32 v2, v5, v2
	v_add_f32_e32 v5, v2, v3
	ds_read2st64_b32 v[2:3], v4 offset0:100 offset1:105
	s_waitcnt lgkmcnt(0)
	v_add_f32_e32 v2, v5, v2
	v_add_f32_e32 v5, v2, v3
	ds_read2st64_b32 v[2:3], v4 offset0:110 offset1:115
	s_waitcnt lgkmcnt(0)
	v_add_f32_e32 v2, v5, v2
	v_add_f32_e32 v5, v2, v3
	ds_read2st64_b32 v[2:3], v4 offset0:120 offset1:125
	s_waitcnt lgkmcnt(0)
	v_add_f32_e32 v2, v5, v2
	v_add_f32_e32 v5, v2, v3
	ds_read2st64_b32 v[2:3], v4 offset0:130 offset1:135
	s_waitcnt lgkmcnt(0)
	v_add_f32_e32 v2, v5, v2
	v_add_f32_e32 v5, v2, v3
	ds_read2st64_b32 v[2:3], v4 offset0:140 offset1:145
	s_waitcnt lgkmcnt(0)
	v_add_f32_e32 v2, v5, v2
	v_add_f32_e32 v5, v2, v3
	ds_read2st64_b32 v[2:3], v4 offset0:150 offset1:155
	s_waitcnt lgkmcnt(0)
	v_add_f32_e32 v2, v5, v2
	v_add_f32_e32 v5, v2, v3
	ds_read2st64_b32 v[2:3], v4 offset0:160 offset1:165
	s_waitcnt lgkmcnt(0)
	v_add_f32_e32 v2, v5, v2
	v_add_f32_e32 v5, v2, v3
	ds_read2st64_b32 v[2:3], v4 offset0:170 offset1:175
	s_waitcnt lgkmcnt(0)
	v_add_f32_e32 v2, v5, v2
	v_add_f32_e32 v5, v2, v3
	ds_read2st64_b32 v[2:3], v4 offset0:180 offset1:185
	s_waitcnt lgkmcnt(0)
	v_add_f32_e32 v2, v5, v2
	v_add_f32_e32 v5, v2, v3
	ds_read2st64_b32 v[2:3], v4 offset0:190 offset1:195
	s_waitcnt lgkmcnt(0)
	v_add_f32_e32 v2, v5, v2
	v_add_f32_e32 v5, v2, v3
	ds_read2st64_b32 v[2:3], v4 offset0:200 offset1:205
	s_waitcnt lgkmcnt(0)
	v_add_f32_e32 v2, v5, v2
	v_add_f32_e32 v5, v2, v3
	ds_read2st64_b32 v[2:3], v4 offset0:210 offset1:215
	s_waitcnt lgkmcnt(0)
	v_add_f32_e32 v2, v5, v2
	v_add_f32_e32 v5, v2, v3
	ds_read2st64_b32 v[2:3], v4 offset0:220 offset1:225
	s_waitcnt lgkmcnt(0)
	v_add_f32_e32 v2, v5, v2
	v_add_f32_e32 v5, v2, v3
	ds_read2st64_b32 v[2:3], v4 offset0:230 offset1:235
	s_waitcnt lgkmcnt(0)
	v_add_f32_e32 v2, v5, v2
	v_add_f32_e32 v6, v2, v3
	v_or_b32_e32 v2, s6, v1
	s_mul_i32 s6, s4, 0x6000
	v_ashrrev_i32_e32 v3, 31, v2
	s_add_u32 s6, s22, s6
	s_addc_u32 s7, s23, s5
	v_lshlrev_b64 v[2:3], 2, v[2:3]
	v_lshl_add_u64 v[4:5], s[6:7], 0, v[2:3]
	global_load_dword v1, v[4:5], off
	v_mov_b64_e32 v[4:5], s[66:67]
	s_waitcnt vmcnt(0)
	v_add_f32_e32 v6, v6, v1
	v_ashrrev_i32_e32 v1, 31, v0
	v_mad_i64_i32 v[0:1], s[4:5], s4, 5, v[0:1]
	v_mad_u64_u32 v[4:5], s[4:5], v0, s28, v[4:5]
	v_mad_i32_i24 v5, v1, s28, v5
	v_lshl_add_u64 v[0:1], v[4:5], 0, v[2:3]
	global_store_dword v[0:1], v6, off sc1
	s_branch .LBB0_388
